# RW scan inner loops rewritten by hand: 49 instr/step (was 62), operand loads one step ahead with immediate LDS offsets, running store pointer
# speedup vs baseline: 1.0011x; 1.0011x over previous
.LBB0_859:
	v_mov_b32_e32 v136, v100
	v_mov_b32_e32 v137, v101
	v_mov_b32_e32 v138, 0
	s_lshl_b32 s100, s2, 9
	s_ashr_i32 s101, s100, 31
.Lrwscan_859:
	s_waitcnt lgkmcnt(0)
	v_pk_fma_f32 v[106:107], v[84:85], v[34:35], 0 op_sel_hi:[1,1,0]
	v_pk_fma_f32 v[108:109], v[84:85], v[22:23], 0 op_sel_hi:[1,1,0]
	ds_read_b128 v[70:73], v136 offset:1568
	ds_read_b128 v[66:69], v136 offset:1584
	v_pk_fma_f32 v[106:107], v[86:87], v[36:37], v[106:107]
	v_pk_fma_f32 v[108:109], v[86:87], v[24:25], v[108:109]
	ds_read_b128 v[50:53], v136 offset:1824
	ds_read_b128 v[46:49], v136 offset:1840
	v_pk_fma_f32 v[106:107], v[88:89], v[38:39], v[106:107]
	v_pk_fma_f32 v[108:109], v[88:89], v[18:19], v[108:109]
	ds_read_b128 v[54:57], v136 offset:2080
	ds_read_b128 v[42:45], v136 offset:2096
	v_pk_fma_f32 v[106:107], v[90:91], v[40:41], v[106:107]
	v_pk_fma_f32 v[108:109], v[90:91], v[20:21], v[108:109]
	ds_read_b128 v[78:81], v136 offset:2336
	ds_read_b128 v[74:77], v136 offset:2352
	v_add_f32_e32 v130, v106, v107
	v_add_f32_e32 v131, v108, v109
	v_pk_mul_f32 v[114:115], v[84:85], v[2:3]
	v_add_f32_dpp v130, v130, v130 quad_perm:[1,0,3,2] row_mask:0xf bank_mask:0xf bound_ctrl:1
	v_add_f32_dpp v131, v131, v131 quad_perm:[1,0,3,2] row_mask:0xf bank_mask:0xf bound_ctrl:1
	v_pk_mul_f32 v[116:117], v[86:87], v[4:5]
	v_add_f32_dpp v130, v130, v130 quad_perm:[2,3,0,1] row_mask:0xf bank_mask:0xf bound_ctrl:1
	v_add_f32_dpp v131, v131, v131 quad_perm:[2,3,0,1] row_mask:0xf bank_mask:0xf bound_ctrl:1
	v_pk_mul_f32 v[118:119], v[88:89], v[6:7]
	v_add_f32_dpp v130, v130, v130 row_half_mirror row_mask:0xf bank_mask:0xf bound_ctrl:1
	v_add_f32_dpp v131, v131, v131 row_half_mirror row_mask:0xf bank_mask:0xf bound_ctrl:1
	v_pk_mul_f32 v[120:121], v[90:91], v[8:9]
	ds_read_b128 v[62:65], v136 offset:2592
	ds_read_b128 v[58:61], v136 offset:2608
	v_mul_f32_e32 v132, v130, v96
	v_mul_f32_e32 v133, v97, v94
	ds_read_b32 v0, v137 offset:2848
	v_add_f32_e32 v131, v132, v131
	ds_read_b64 v[98:99], v138 offset:3104
	v_add_f32_e32 v131, v133, v131
	v_pk_fma_f32 v[114:115], v[130:131], v[26:27], v[114:115] op_sel_hi:[0,1,1]
	v_pk_fma_f32 v[116:117], v[130:131], v[28:29], v[116:117] op_sel_hi:[0,1,1]
	v_bfe_u32 v132, v131, 16, 1
	v_pk_fma_f32 v[84:85], v[94:95], v[10:11], v[114:115] op_sel_hi:[0,1,1]
	v_add3_u32 v132, v131, v132, s28
	global_store_short_d16_hi v[92:93], v132, off
	v_pk_fma_f32 v[118:119], v[130:131], v[30:31], v[118:119] op_sel_hi:[0,1,1]
	v_pk_fma_f32 v[86:87], v[94:95], v[12:13], v[116:117] op_sel_hi:[0,1,1]
	v_pk_fma_f32 v[120:121], v[130:131], v[32:33], v[120:121] op_sel_hi:[0,1,1]
	v_pk_fma_f32 v[88:89], v[94:95], v[14:15], v[118:119] op_sel_hi:[0,1,1]
	v_lshl_add_u64 v[92:93], v[92:93], 0, s[100:101]
	v_pk_fma_f32 v[90:91], v[94:95], v[16:17], v[120:121] op_sel_hi:[0,1,1]
	s_waitcnt lgkmcnt(0)
	v_pk_fma_f32 v[110:111], v[84:85], v[78:79], 0 op_sel_hi:[1,1,0]
	v_pk_fma_f32 v[112:113], v[84:85], v[70:71], 0 op_sel_hi:[1,1,0]
	ds_read_b128 v[22:25], v136 offset:3136
	ds_read_b128 v[18:21], v136 offset:3152
	v_pk_fma_f32 v[110:111], v[86:87], v[80:81], v[110:111]
	v_pk_fma_f32 v[112:113], v[86:87], v[72:73], v[112:113]
	ds_read_b128 v[2:5], v136 offset:3392
	ds_read_b128 v[6:9], v136 offset:3408
	v_pk_fma_f32 v[110:111], v[88:89], v[74:75], v[110:111]
	v_pk_fma_f32 v[112:113], v[88:89], v[66:67], v[112:113]
	ds_read_b128 v[10:13], v136 offset:3648
	ds_read_b128 v[14:17], v136 offset:3664
	v_pk_fma_f32 v[110:111], v[90:91], v[76:77], v[110:111]
	v_pk_fma_f32 v[112:113], v[90:91], v[68:69], v[112:113]
	ds_read_b128 v[34:37], v136 offset:3904
	ds_read_b128 v[38:41], v136 offset:3920
	v_add_f32_e32 v140, v110, v111
	v_add_f32_e32 v141, v112, v113
	v_pk_mul_f32 v[114:115], v[84:85], v[50:51]
	v_add_f32_dpp v140, v140, v140 quad_perm:[1,0,3,2] row_mask:0xf bank_mask:0xf bound_ctrl:1
	v_add_f32_dpp v141, v141, v141 quad_perm:[1,0,3,2] row_mask:0xf bank_mask:0xf bound_ctrl:1
	v_pk_mul_f32 v[116:117], v[86:87], v[52:53]
	v_add_f32_dpp v140, v140, v140 quad_perm:[2,3,0,1] row_mask:0xf bank_mask:0xf bound_ctrl:1
	v_add_f32_dpp v141, v141, v141 quad_perm:[2,3,0,1] row_mask:0xf bank_mask:0xf bound_ctrl:1
	v_pk_mul_f32 v[118:119], v[88:89], v[46:47]
	v_add_f32_dpp v140, v140, v140 row_half_mirror row_mask:0xf bank_mask:0xf bound_ctrl:1
	v_add_f32_dpp v141, v141, v141 row_half_mirror row_mask:0xf bank_mask:0xf bound_ctrl:1
	v_pk_mul_f32 v[120:121], v[90:91], v[48:49]
	ds_read_b128 v[26:29], v136 offset:4160
	ds_read_b128 v[30:33], v136 offset:4176
	v_mul_f32_e32 v142, v140, v98
	v_mul_f32_e32 v143, v99, v0
	ds_read_b32 v94, v137 offset:4416
	v_add_f32_e32 v141, v142, v141
	ds_read_b64 v[96:97], v138 offset:4672
	v_add_f32_e32 v141, v143, v141
	v_pk_fma_f32 v[114:115], v[140:141], v[62:63], v[114:115] op_sel_hi:[0,1,1]
	v_pk_fma_f32 v[116:117], v[140:141], v[64:65], v[116:117] op_sel_hi:[0,1,1]
	v_bfe_u32 v142, v141, 16, 1
	v_pk_fma_f32 v[84:85], v[0:1], v[54:55], v[114:115] op_sel_hi:[0,1,1]
	v_add3_u32 v142, v141, v142, s28
	global_store_short_d16_hi v[92:93], v142, off
	v_pk_fma_f32 v[118:119], v[140:141], v[58:59], v[118:119] op_sel_hi:[0,1,1]
	v_pk_fma_f32 v[86:87], v[0:1], v[56:57], v[116:117] op_sel_hi:[0,1,1]
	v_pk_fma_f32 v[120:121], v[140:141], v[60:61], v[120:121] op_sel_hi:[0,1,1]
	v_pk_fma_f32 v[88:89], v[0:1], v[42:43], v[118:119] op_sel_hi:[0,1,1]
	v_lshl_add_u64 v[92:93], v[92:93], 0, s[100:101]
	v_pk_fma_f32 v[90:91], v[0:1], v[44:45], v[120:121] op_sel_hi:[0,1,1]
	s_waitcnt lgkmcnt(0)
	v_pk_fma_f32 v[106:107], v[84:85], v[34:35], 0 op_sel_hi:[1,1,0]
	v_pk_fma_f32 v[108:109], v[84:85], v[22:23], 0 op_sel_hi:[1,1,0]
	ds_read_b128 v[70:73], v136 offset:4704
	ds_read_b128 v[66:69], v136 offset:4720
	v_pk_fma_f32 v[106:107], v[86:87], v[36:37], v[106:107]
	v_pk_fma_f32 v[108:109], v[86:87], v[24:25], v[108:109]
	ds_read_b128 v[50:53], v136 offset:4960
	ds_read_b128 v[46:49], v136 offset:4976
	v_pk_fma_f32 v[106:107], v[88:89], v[38:39], v[106:107]
	v_pk_fma_f32 v[108:109], v[88:89], v[18:19], v[108:109]
	ds_read_b128 v[54:57], v136 offset:5216
	ds_read_b128 v[42:45], v136 offset:5232
	v_pk_fma_f32 v[106:107], v[90:91], v[40:41], v[106:107]
	v_pk_fma_f32 v[108:109], v[90:91], v[20:21], v[108:109]
	ds_read_b128 v[78:81], v136 offset:5472
	ds_read_b128 v[74:77], v136 offset:5488
	v_add_f32_e32 v130, v106, v107
	v_add_f32_e32 v131, v108, v109
	v_pk_mul_f32 v[114:115], v[84:85], v[2:3]
	v_add_f32_dpp v130, v130, v130 quad_perm:[1,0,3,2] row_mask:0xf bank_mask:0xf bound_ctrl:1
	v_add_f32_dpp v131, v131, v131 quad_perm:[1,0,3,2] row_mask:0xf bank_mask:0xf bound_ctrl:1
	v_pk_mul_f32 v[116:117], v[86:87], v[4:5]
	v_add_f32_dpp v130, v130, v130 quad_perm:[2,3,0,1] row_mask:0xf bank_mask:0xf bound_ctrl:1
	v_add_f32_dpp v131, v131, v131 quad_perm:[2,3,0,1] row_mask:0xf bank_mask:0xf bound_ctrl:1
	v_pk_mul_f32 v[118:119], v[88:89], v[6:7]
	v_add_f32_dpp v130, v130, v130 row_half_mirror row_mask:0xf bank_mask:0xf bound_ctrl:1
	v_add_f32_dpp v131, v131, v131 row_half_mirror row_mask:0xf bank_mask:0xf bound_ctrl:1
	v_pk_mul_f32 v[120:121], v[90:91], v[8:9]
	ds_read_b128 v[62:65], v136 offset:5728
	ds_read_b128 v[58:61], v136 offset:5744
	v_mul_f32_e32 v132, v130, v96
	v_mul_f32_e32 v133, v97, v94
	ds_read_b32 v0, v137 offset:5984
	v_add_f32_e32 v131, v132, v131
	ds_read_b64 v[98:99], v138 offset:6240
	v_add_f32_e32 v131, v133, v131
	v_pk_fma_f32 v[114:115], v[130:131], v[26:27], v[114:115] op_sel_hi:[0,1,1]
	v_pk_fma_f32 v[116:117], v[130:131], v[28:29], v[116:117] op_sel_hi:[0,1,1]
	v_bfe_u32 v132, v131, 16, 1
	v_pk_fma_f32 v[84:85], v[94:95], v[10:11], v[114:115] op_sel_hi:[0,1,1]
	v_add3_u32 v132, v131, v132, s28
	global_store_short_d16_hi v[92:93], v132, off
	v_pk_fma_f32 v[118:119], v[130:131], v[30:31], v[118:119] op_sel_hi:[0,1,1]
	v_pk_fma_f32 v[86:87], v[94:95], v[12:13], v[116:117] op_sel_hi:[0,1,1]
	v_pk_fma_f32 v[120:121], v[130:131], v[32:33], v[120:121] op_sel_hi:[0,1,1]
	v_pk_fma_f32 v[88:89], v[94:95], v[14:15], v[118:119] op_sel_hi:[0,1,1]
	v_lshl_add_u64 v[92:93], v[92:93], 0, s[100:101]
	v_pk_fma_f32 v[90:91], v[94:95], v[16:17], v[120:121] op_sel_hi:[0,1,1]
	s_waitcnt lgkmcnt(0)
	v_pk_fma_f32 v[110:111], v[84:85], v[78:79], 0 op_sel_hi:[1,1,0]
	v_pk_fma_f32 v[112:113], v[84:85], v[70:71], 0 op_sel_hi:[1,1,0]
	ds_read_b128 v[22:25], v136 offset:6272
	ds_read_b128 v[18:21], v136 offset:6288
	v_pk_fma_f32 v[110:111], v[86:87], v[80:81], v[110:111]
	v_pk_fma_f32 v[112:113], v[86:87], v[72:73], v[112:113]
	ds_read_b128 v[2:5], v136 offset:6528
	ds_read_b128 v[6:9], v136 offset:6544
	v_pk_fma_f32 v[110:111], v[88:89], v[74:75], v[110:111]
	v_pk_fma_f32 v[112:113], v[88:89], v[66:67], v[112:113]
	ds_read_b128 v[10:13], v136 offset:6784
	ds_read_b128 v[14:17], v136 offset:6800
	v_pk_fma_f32 v[110:111], v[90:91], v[76:77], v[110:111]
	v_pk_fma_f32 v[112:113], v[90:91], v[68:69], v[112:113]
	ds_read_b128 v[34:37], v136 offset:7040
	ds_read_b128 v[38:41], v136 offset:7056
	v_add_f32_e32 v140, v110, v111
	v_add_f32_e32 v141, v112, v113
	v_pk_mul_f32 v[114:115], v[84:85], v[50:51]
	v_add_f32_dpp v140, v140, v140 quad_perm:[1,0,3,2] row_mask:0xf bank_mask:0xf bound_ctrl:1
	v_add_f32_dpp v141, v141, v141 quad_perm:[1,0,3,2] row_mask:0xf bank_mask:0xf bound_ctrl:1
	v_pk_mul_f32 v[116:117], v[86:87], v[52:53]
	v_add_f32_dpp v140, v140, v140 quad_perm:[2,3,0,1] row_mask:0xf bank_mask:0xf bound_ctrl:1
	v_add_f32_dpp v141, v141, v141 quad_perm:[2,3,0,1] row_mask:0xf bank_mask:0xf bound_ctrl:1
	v_pk_mul_f32 v[118:119], v[88:89], v[46:47]
	v_add_f32_dpp v140, v140, v140 row_half_mirror row_mask:0xf bank_mask:0xf bound_ctrl:1
	v_add_f32_dpp v141, v141, v141 row_half_mirror row_mask:0xf bank_mask:0xf bound_ctrl:1
	v_pk_mul_f32 v[120:121], v[90:91], v[48:49]
	ds_read_b128 v[26:29], v136 offset:7296
	ds_read_b128 v[30:33], v136 offset:7312
	v_mul_f32_e32 v142, v140, v98
	v_mul_f32_e32 v143, v99, v0
	ds_read_b32 v94, v137 offset:7552
	v_add_f32_e32 v141, v142, v141
	ds_read_b64 v[96:97], v138 offset:7808
	v_add_f32_e32 v141, v143, v141
	v_pk_fma_f32 v[114:115], v[140:141], v[62:63], v[114:115] op_sel_hi:[0,1,1]
	v_pk_fma_f32 v[116:117], v[140:141], v[64:65], v[116:117] op_sel_hi:[0,1,1]
	v_bfe_u32 v142, v141, 16, 1
	v_pk_fma_f32 v[84:85], v[0:1], v[54:55], v[114:115] op_sel_hi:[0,1,1]
	v_add3_u32 v142, v141, v142, s28
	global_store_short_d16_hi v[92:93], v142, off
	v_pk_fma_f32 v[118:119], v[140:141], v[58:59], v[118:119] op_sel_hi:[0,1,1]
	v_pk_fma_f32 v[86:87], v[0:1], v[56:57], v[116:117] op_sel_hi:[0,1,1]
	v_pk_fma_f32 v[120:121], v[140:141], v[60:61], v[120:121] op_sel_hi:[0,1,1]
	v_pk_fma_f32 v[88:89], v[0:1], v[42:43], v[118:119] op_sel_hi:[0,1,1]
	v_lshl_add_u64 v[92:93], v[92:93], 0, s[100:101]
	v_pk_fma_f32 v[90:91], v[0:1], v[44:45], v[120:121] op_sel_hi:[0,1,1]
	v_add_u32_e32 v136, 0x1880, v136
	v_add_u32_e32 v137, 0x1880, v137
	v_add_u32_e32 v138, 0x1880, v138
	s_add_i32 s10, s10, 4
	s_cmp_lt_i32 s10, 14
	s_cbranch_scc1 .Lrwscan_859

.LBB0_869:
	v_add_u32_e32 v136, 0x6200, v100
	v_add_u32_e32 v137, 0x6200, v101
	v_mov_b32_e32 v138, 0x6200
	s_lshl_b32 s100, s2, 9
	s_ashr_i32 s101, s100, 31
.Lrwscan_869:
	s_waitcnt lgkmcnt(0)
	v_pk_fma_f32 v[106:107], v[84:85], v[34:35], 0 op_sel_hi:[1,1,0]
	v_pk_fma_f32 v[108:109], v[84:85], v[22:23], 0 op_sel_hi:[1,1,0]
	ds_read_b128 v[70:73], v136 offset:1568
	ds_read_b128 v[66:69], v136 offset:1584
	v_pk_fma_f32 v[106:107], v[86:87], v[36:37], v[106:107]
	v_pk_fma_f32 v[108:109], v[86:87], v[24:25], v[108:109]
	ds_read_b128 v[50:53], v136 offset:1824
	ds_read_b128 v[46:49], v136 offset:1840
	v_pk_fma_f32 v[106:107], v[88:89], v[38:39], v[106:107]
	v_pk_fma_f32 v[108:109], v[88:89], v[18:19], v[108:109]
	ds_read_b128 v[54:57], v136 offset:2080
	ds_read_b128 v[42:45], v136 offset:2096
	v_pk_fma_f32 v[106:107], v[90:91], v[40:41], v[106:107]
	v_pk_fma_f32 v[108:109], v[90:91], v[20:21], v[108:109]
	ds_read_b128 v[78:81], v136 offset:2336
	ds_read_b128 v[74:77], v136 offset:2352
	v_add_f32_e32 v130, v106, v107
	v_add_f32_e32 v131, v108, v109
	v_pk_mul_f32 v[114:115], v[84:85], v[2:3]
	v_add_f32_dpp v130, v130, v130 quad_perm:[1,0,3,2] row_mask:0xf bank_mask:0xf bound_ctrl:1
	v_add_f32_dpp v131, v131, v131 quad_perm:[1,0,3,2] row_mask:0xf bank_mask:0xf bound_ctrl:1
	v_pk_mul_f32 v[116:117], v[86:87], v[4:5]
	v_add_f32_dpp v130, v130, v130 quad_perm:[2,3,0,1] row_mask:0xf bank_mask:0xf bound_ctrl:1
	v_add_f32_dpp v131, v131, v131 quad_perm:[2,3,0,1] row_mask:0xf bank_mask:0xf bound_ctrl:1
	v_pk_mul_f32 v[118:119], v[88:89], v[6:7]
	v_add_f32_dpp v130, v130, v130 row_half_mirror row_mask:0xf bank_mask:0xf bound_ctrl:1
	v_add_f32_dpp v131, v131, v131 row_half_mirror row_mask:0xf bank_mask:0xf bound_ctrl:1
	v_pk_mul_f32 v[120:121], v[90:91], v[8:9]
	ds_read_b128 v[62:65], v136 offset:2592
	ds_read_b128 v[58:61], v136 offset:2608
	v_mul_f32_e32 v132, v130, v96
	v_mul_f32_e32 v133, v97, v94
	ds_read_b32 v0, v137 offset:2848
	v_add_f32_e32 v131, v132, v131
	ds_read_b64 v[98:99], v138 offset:3104
	v_add_f32_e32 v131, v133, v131
	v_pk_fma_f32 v[114:115], v[130:131], v[26:27], v[114:115] op_sel_hi:[0,1,1]
	v_pk_fma_f32 v[116:117], v[130:131], v[28:29], v[116:117] op_sel_hi:[0,1,1]
	v_bfe_u32 v132, v131, 16, 1
	v_pk_fma_f32 v[84:85], v[94:95], v[10:11], v[114:115] op_sel_hi:[0,1,1]
	v_add3_u32 v132, v131, v132, s28
	global_store_short_d16_hi v[92:93], v132, off
	v_pk_fma_f32 v[118:119], v[130:131], v[30:31], v[118:119] op_sel_hi:[0,1,1]
	v_pk_fma_f32 v[86:87], v[94:95], v[12:13], v[116:117] op_sel_hi:[0,1,1]
	v_pk_fma_f32 v[120:121], v[130:131], v[32:33], v[120:121] op_sel_hi:[0,1,1]
	v_pk_fma_f32 v[88:89], v[94:95], v[14:15], v[118:119] op_sel_hi:[0,1,1]
	v_lshl_add_u64 v[92:93], v[92:93], 0, s[100:101]
	v_pk_fma_f32 v[90:91], v[94:95], v[16:17], v[120:121] op_sel_hi:[0,1,1]
	s_waitcnt lgkmcnt(0)
	v_pk_fma_f32 v[110:111], v[84:85], v[78:79], 0 op_sel_hi:[1,1,0]
	v_pk_fma_f32 v[112:113], v[84:85], v[70:71], 0 op_sel_hi:[1,1,0]
	ds_read_b128 v[22:25], v136 offset:3136
	ds_read_b128 v[18:21], v136 offset:3152
	v_pk_fma_f32 v[110:111], v[86:87], v[80:81], v[110:111]
	v_pk_fma_f32 v[112:113], v[86:87], v[72:73], v[112:113]
	ds_read_b128 v[2:5], v136 offset:3392
	ds_read_b128 v[6:9], v136 offset:3408
	v_pk_fma_f32 v[110:111], v[88:89], v[74:75], v[110:111]
	v_pk_fma_f32 v[112:113], v[88:89], v[66:67], v[112:113]
	ds_read_b128 v[10:13], v136 offset:3648
	ds_read_b128 v[14:17], v136 offset:3664
	v_pk_fma_f32 v[110:111], v[90:91], v[76:77], v[110:111]
	v_pk_fma_f32 v[112:113], v[90:91], v[68:69], v[112:113]
	ds_read_b128 v[34:37], v136 offset:3904
	ds_read_b128 v[38:41], v136 offset:3920
	v_add_f32_e32 v140, v110, v111
	v_add_f32_e32 v141, v112, v113
	v_pk_mul_f32 v[114:115], v[84:85], v[50:51]
	v_add_f32_dpp v140, v140, v140 quad_perm:[1,0,3,2] row_mask:0xf bank_mask:0xf bound_ctrl:1
	v_add_f32_dpp v141, v141, v141 quad_perm:[1,0,3,2] row_mask:0xf bank_mask:0xf bound_ctrl:1
	v_pk_mul_f32 v[116:117], v[86:87], v[52:53]
	v_add_f32_dpp v140, v140, v140 quad_perm:[2,3,0,1] row_mask:0xf bank_mask:0xf bound_ctrl:1
	v_add_f32_dpp v141, v141, v141 quad_perm:[2,3,0,1] row_mask:0xf bank_mask:0xf bound_ctrl:1
	v_pk_mul_f32 v[118:119], v[88:89], v[46:47]
	v_add_f32_dpp v140, v140, v140 row_half_mirror row_mask:0xf bank_mask:0xf bound_ctrl:1
	v_add_f32_dpp v141, v141, v141 row_half_mirror row_mask:0xf bank_mask:0xf bound_ctrl:1
	v_pk_mul_f32 v[120:121], v[90:91], v[48:49]
	ds_read_b128 v[26:29], v136 offset:4160
	ds_read_b128 v[30:33], v136 offset:4176
	v_mul_f32_e32 v142, v140, v98
	v_mul_f32_e32 v143, v99, v0
	ds_read_b32 v94, v137 offset:4416
	v_add_f32_e32 v141, v142, v141
	ds_read_b64 v[96:97], v138 offset:4672
	v_add_f32_e32 v141, v143, v141
	v_pk_fma_f32 v[114:115], v[140:141], v[62:63], v[114:115] op_sel_hi:[0,1,1]
	v_pk_fma_f32 v[116:117], v[140:141], v[64:65], v[116:117] op_sel_hi:[0,1,1]
	v_bfe_u32 v142, v141, 16, 1
	v_pk_fma_f32 v[84:85], v[0:1], v[54:55], v[114:115] op_sel_hi:[0,1,1]
	v_add3_u32 v142, v141, v142, s28
	global_store_short_d16_hi v[92:93], v142, off
	v_pk_fma_f32 v[118:119], v[140:141], v[58:59], v[118:119] op_sel_hi:[0,1,1]
	v_pk_fma_f32 v[86:87], v[0:1], v[56:57], v[116:117] op_sel_hi:[0,1,1]
	v_pk_fma_f32 v[120:121], v[140:141], v[60:61], v[120:121] op_sel_hi:[0,1,1]
	v_pk_fma_f32 v[88:89], v[0:1], v[42:43], v[118:119] op_sel_hi:[0,1,1]
	v_lshl_add_u64 v[92:93], v[92:93], 0, s[100:101]
	v_pk_fma_f32 v[90:91], v[0:1], v[44:45], v[120:121] op_sel_hi:[0,1,1]
	s_waitcnt lgkmcnt(0)
	v_pk_fma_f32 v[106:107], v[84:85], v[34:35], 0 op_sel_hi:[1,1,0]
	v_pk_fma_f32 v[108:109], v[84:85], v[22:23], 0 op_sel_hi:[1,1,0]
	ds_read_b128 v[70:73], v136 offset:4704
	ds_read_b128 v[66:69], v136 offset:4720
	v_pk_fma_f32 v[106:107], v[86:87], v[36:37], v[106:107]
	v_pk_fma_f32 v[108:109], v[86:87], v[24:25], v[108:109]
	ds_read_b128 v[50:53], v136 offset:4960
	ds_read_b128 v[46:49], v136 offset:4976
	v_pk_fma_f32 v[106:107], v[88:89], v[38:39], v[106:107]
	v_pk_fma_f32 v[108:109], v[88:89], v[18:19], v[108:109]
	ds_read_b128 v[54:57], v136 offset:5216
	ds_read_b128 v[42:45], v136 offset:5232
	v_pk_fma_f32 v[106:107], v[90:91], v[40:41], v[106:107]
	v_pk_fma_f32 v[108:109], v[90:91], v[20:21], v[108:109]
	ds_read_b128 v[78:81], v136 offset:5472
	ds_read_b128 v[74:77], v136 offset:5488
	v_add_f32_e32 v130, v106, v107
	v_add_f32_e32 v131, v108, v109
	v_pk_mul_f32 v[114:115], v[84:85], v[2:3]
	v_add_f32_dpp v130, v130, v130 quad_perm:[1,0,3,2] row_mask:0xf bank_mask:0xf bound_ctrl:1
	v_add_f32_dpp v131, v131, v131 quad_perm:[1,0,3,2] row_mask:0xf bank_mask:0xf bound_ctrl:1
	v_pk_mul_f32 v[116:117], v[86:87], v[4:5]
	v_add_f32_dpp v130, v130, v130 quad_perm:[2,3,0,1] row_mask:0xf bank_mask:0xf bound_ctrl:1
	v_add_f32_dpp v131, v131, v131 quad_perm:[2,3,0,1] row_mask:0xf bank_mask:0xf bound_ctrl:1
	v_pk_mul_f32 v[118:119], v[88:89], v[6:7]
	v_add_f32_dpp v130, v130, v130 row_half_mirror row_mask:0xf bank_mask:0xf bound_ctrl:1
	v_add_f32_dpp v131, v131, v131 row_half_mirror row_mask:0xf bank_mask:0xf bound_ctrl:1
	v_pk_mul_f32 v[120:121], v[90:91], v[8:9]
	ds_read_b128 v[62:65], v136 offset:5728
	ds_read_b128 v[58:61], v136 offset:5744
	v_mul_f32_e32 v132, v130, v96
	v_mul_f32_e32 v133, v97, v94
	ds_read_b32 v0, v137 offset:5984
	v_add_f32_e32 v131, v132, v131
	ds_read_b64 v[98:99], v138 offset:6240
	v_add_f32_e32 v131, v133, v131
	v_pk_fma_f32 v[114:115], v[130:131], v[26:27], v[114:115] op_sel_hi:[0,1,1]
	v_pk_fma_f32 v[116:117], v[130:131], v[28:29], v[116:117] op_sel_hi:[0,1,1]
	v_bfe_u32 v132, v131, 16, 1
	v_pk_fma_f32 v[84:85], v[94:95], v[10:11], v[114:115] op_sel_hi:[0,1,1]
	v_add3_u32 v132, v131, v132, s28
	global_store_short_d16_hi v[92:93], v132, off
	v_pk_fma_f32 v[118:119], v[130:131], v[30:31], v[118:119] op_sel_hi:[0,1,1]
	v_pk_fma_f32 v[86:87], v[94:95], v[12:13], v[116:117] op_sel_hi:[0,1,1]
	v_pk_fma_f32 v[120:121], v[130:131], v[32:33], v[120:121] op_sel_hi:[0,1,1]
	v_pk_fma_f32 v[88:89], v[94:95], v[14:15], v[118:119] op_sel_hi:[0,1,1]
	v_lshl_add_u64 v[92:93], v[92:93], 0, s[100:101]
	v_pk_fma_f32 v[90:91], v[94:95], v[16:17], v[120:121] op_sel_hi:[0,1,1]
	s_waitcnt lgkmcnt(0)
	v_pk_fma_f32 v[110:111], v[84:85], v[78:79], 0 op_sel_hi:[1,1,0]
	v_pk_fma_f32 v[112:113], v[84:85], v[70:71], 0 op_sel_hi:[1,1,0]
	ds_read_b128 v[22:25], v136 offset:6272
	ds_read_b128 v[18:21], v136 offset:6288
	v_pk_fma_f32 v[110:111], v[86:87], v[80:81], v[110:111]
	v_pk_fma_f32 v[112:113], v[86:87], v[72:73], v[112:113]
	ds_read_b128 v[2:5], v136 offset:6528
	ds_read_b128 v[6:9], v136 offset:6544
	v_pk_fma_f32 v[110:111], v[88:89], v[74:75], v[110:111]
	v_pk_fma_f32 v[112:113], v[88:89], v[66:67], v[112:113]
	ds_read_b128 v[10:13], v136 offset:6784
	ds_read_b128 v[14:17], v136 offset:6800
	v_pk_fma_f32 v[110:111], v[90:91], v[76:77], v[110:111]
	v_pk_fma_f32 v[112:113], v[90:91], v[68:69], v[112:113]
	ds_read_b128 v[34:37], v136 offset:7040
	ds_read_b128 v[38:41], v136 offset:7056
	v_add_f32_e32 v140, v110, v111
	v_add_f32_e32 v141, v112, v113
	v_pk_mul_f32 v[114:115], v[84:85], v[50:51]
	v_add_f32_dpp v140, v140, v140 quad_perm:[1,0,3,2] row_mask:0xf bank_mask:0xf bound_ctrl:1
	v_add_f32_dpp v141, v141, v141 quad_perm:[1,0,3,2] row_mask:0xf bank_mask:0xf bound_ctrl:1
	v_pk_mul_f32 v[116:117], v[86:87], v[52:53]
	v_add_f32_dpp v140, v140, v140 quad_perm:[2,3,0,1] row_mask:0xf bank_mask:0xf bound_ctrl:1
	v_add_f32_dpp v141, v141, v141 quad_perm:[2,3,0,1] row_mask:0xf bank_mask:0xf bound_ctrl:1
	v_pk_mul_f32 v[118:119], v[88:89], v[46:47]
	v_add_f32_dpp v140, v140, v140 row_half_mirror row_mask:0xf bank_mask:0xf bound_ctrl:1
	v_add_f32_dpp v141, v141, v141 row_half_mirror row_mask:0xf bank_mask:0xf bound_ctrl:1
	v_pk_mul_f32 v[120:121], v[90:91], v[48:49]
	ds_read_b128 v[26:29], v136 offset:7296
	ds_read_b128 v[30:33], v136 offset:7312
	v_mul_f32_e32 v142, v140, v98
	v_mul_f32_e32 v143, v99, v0
	ds_read_b32 v94, v137 offset:7552
	v_add_f32_e32 v141, v142, v141
	ds_read_b64 v[96:97], v138 offset:7808
	v_add_f32_e32 v141, v143, v141
	v_pk_fma_f32 v[114:115], v[140:141], v[62:63], v[114:115] op_sel_hi:[0,1,1]
	v_pk_fma_f32 v[116:117], v[140:141], v[64:65], v[116:117] op_sel_hi:[0,1,1]
	v_bfe_u32 v142, v141, 16, 1
	v_pk_fma_f32 v[84:85], v[0:1], v[54:55], v[114:115] op_sel_hi:[0,1,1]
	v_add3_u32 v142, v141, v142, s28
	global_store_short_d16_hi v[92:93], v142, off
	v_pk_fma_f32 v[118:119], v[140:141], v[58:59], v[118:119] op_sel_hi:[0,1,1]
	v_pk_fma_f32 v[86:87], v[0:1], v[56:57], v[116:117] op_sel_hi:[0,1,1]
	v_pk_fma_f32 v[120:121], v[140:141], v[60:61], v[120:121] op_sel_hi:[0,1,1]
	v_pk_fma_f32 v[88:89], v[0:1], v[42:43], v[118:119] op_sel_hi:[0,1,1]
	v_lshl_add_u64 v[92:93], v[92:93], 0, s[100:101]
	v_pk_fma_f32 v[90:91], v[0:1], v[44:45], v[120:121] op_sel_hi:[0,1,1]
	v_add_u32_e32 v136, 0x1880, v136
	v_add_u32_e32 v137, 0x1880, v137
	v_add_u32_e32 v138, 0x1880, v138
	s_add_i32 s7, s7, 4
	s_cmp_lt_i32 s7, 14
	s_cbranch_scc1 .Lrwscan_869
	s_branch .LBB0_852
